# memory K/V epilogue f32 outputs: lane exchange (permlane16/32 swap) so each store writes 64 contiguous bytes per row
# baseline (speedup 1.0000x reference)
.LBB0_1088:
	s_and_b64 vcc, exec, s[50:51]
	s_cbranch_vccz .LBB0_1085
	v_bfe_u32 v178, v214, 4, 2
	v_lshlrev_b32_e32 v178, 4, v178
	v_sub_u32_e32 v178, 0, v178
	v_ashrrev_i32_e32 v179, 31, v178
	s_waitcnt lgkmcnt(0)
	v_lshl_add_u64 v[128:129], v[144:145], 2, s[90:91]
	global_load_dword v130, v[128:129], off
	s_lshl_b32 s0, s66, 3
	v_add_u32_e32 v131, s4, v174
	s_add_i32 s16, s81, s0
	s_movk_i32 s0, 0x3ff
	v_cmp_lt_i32_e32 vcc, s0, v131
	s_movk_i32 s0, 0x400
	v_cmp_gt_i32_e64 s[0:1], s0, v131
	s_ashr_i32 s67, s66, 31
	v_mov_b32_e32 v129, v193
	v_cndmask_b32_e64 v128, v238, v239, s[0:1]
	s_lshl_b64 s[20:21], s[66:67], 23
	v_lshl_add_u64 v[128:129], s[86:87], 0, v[128:129]
	v_lshlrev_b64 v[146:147], 12, v[144:145]
	v_and_b32_e32 v132, 0x3ff, v131
	v_lshlrev_b32_e32 v131, 8, v131
	s_ashr_i32 s17, s16, 31
	v_lshl_add_u64 v[142:143], v[128:129], 0, s[20:21]
	v_mov_b32_e32 v139, v193
	v_lshlrev_b32_e32 v138, 2, v132
	v_and_b32_e32 v131, 0x30000, v131
	s_lshl_b64 s[30:31], s[16:17], 18
	v_lshl_add_u64 v[128:129], v[142:143], 0, v[146:147]
	v_or_b32_e32 v150, s30, v131
	v_mov_b32_e32 v151, s31
	v_lshl_add_u64 v[140:141], v[128:129], 0, v[138:139]
	v_ashrrev_i32_e32 v173, 31, v172
	v_lshlrev_b32_sdwa v136, v240, v174 dst_sel:DWORD dst_unused:UNUSED_PAD src0_sel:DWORD src1_sel:BYTE_0
	s_waitcnt vmcnt(0) lgkmcnt(0)
	v_fmamk_f32 v130, v130, 0x3a800000, v215
	v_rsq_f32_e32 v148, v130
	s_nop 0
	v_pk_mul_f32 v[134:135], v[126:127], v[148:149] op_sel_hi:[1,0]
	v_pk_mul_f32 v[132:133], v[124:125], v[148:149] op_sel_hi:[1,0]
	v_pk_mul_f32 v[130:131], v[122:123], v[148:149] op_sel_hi:[1,0]
	v_pk_mul_f32 v[128:129], v[120:121], v[148:149] op_sel_hi:[1,0]
	v_mov_b32_e32 v184, v132
	v_mov_b32_e32 v185, v133
	v_mov_b32_e32 v186, v134
	v_mov_b32_e32 v187, v135
	v_mov_b32_e32 v188, v128
	v_mov_b32_e32 v189, v129
	v_mov_b32_e32 v190, v130
	v_mov_b32_e32 v191, v131
	s_nop 1
	v_permlane16_swap_b32_e32 v184, v188
	v_permlane16_swap_b32_e32 v185, v189
	v_permlane16_swap_b32_e32 v186, v190
	v_permlane16_swap_b32_e32 v187, v191
	s_nop 1
	v_permlane32_swap_b32_e32 v184, v188
	v_permlane32_swap_b32_e32 v185, v189
	v_permlane32_swap_b32_e32 v186, v190
	v_permlane32_swap_b32_e32 v187, v191
	v_lshl_add_u64 v[182:183], v[140:141], 0, v[178:179]
	global_store_dwordx4 v[182:183], v[184:187], off
	global_store_dwordx4 v[182:183], v[188:191], off offset:64
	v_lshl_add_u64 v[140:141], v[150:151], 1, s[96:97]
	s_and_saveexec_b64 s[0:1], vcc
	s_xor_b64 s[0:1], exec, s[0:1]
	s_cbranch_execz .LBB0_1091
	v_mov_b32_e32 v137, v193
	v_lshl_add_u64 v[144:145], v[140:141], 0, v[136:137]
	v_lshl_add_u64 v[144:145], v[172:173], 1, v[144:145]
	v_cvt_pk_bf16_f32 v128, v128, s0
	global_store_short v[144:145], v128, off offset:2048
	v_cvt_pk_bf16_f32 v128, v133, s0
	global_store_short v[144:145], v128, off offset:512
	v_cvt_pk_bf16_f32 v128, v129, s0
	global_store_short v[144:145], v128, off offset:2560
	v_cvt_pk_bf16_f32 v128, v134, s0
	global_store_short v[144:145], v128, off offset:1024
	v_cvt_pk_bf16_f32 v128, v130, s0
	global_store_short v[144:145], v128, off offset:3072
	v_cvt_pk_bf16_f32 v128, v135, s0
	v_cvt_pk_bf16_f32 v132, v132, s0
	global_store_short v[144:145], v128, off offset:1536
	v_cvt_pk_bf16_f32 v128, v131, s0
	global_store_short v[144:145], v132, off
	global_store_short v[144:145], v128, off offset:3584

.LBB0_1093:
	s_or_b64 exec, exec, s[0:1]
	v_add_u32_e32 v137, 0x80, v174
	v_add_u32_e32 v139, s4, v137
	s_movk_i32 s4, 0x400
	v_mov_b32_e32 v149, v148
	v_mov_b32_e32 v132, v148
	v_mov_b32_e32 v133, v148
	v_cmp_gt_i32_e64 s[4:5], s4, v139
	v_pk_mul_f32 v[130:131], v[94:95], v[132:133]
	v_pk_mul_f32 v[128:129], v[92:93], v[148:149]
	v_pk_mul_f32 v[134:135], v[90:91], v[132:133]
	v_pk_mul_f32 v[132:133], v[88:89], v[148:149]
	v_cndmask_b32_e64 v148, v238, v239, s[4:5]
	v_mov_b32_e32 v149, v193
	s_movk_i32 s0, 0x3ff
	v_lshl_add_u64 v[148:149], s[86:87], 0, v[148:149]
	v_cmp_lt_i32_e64 s[0:1], s0, v139
	v_lshl_add_u64 v[152:153], v[148:149], 0, s[20:21]
	v_and_b32_e32 v145, 0x3ff, v139
	v_lshlrev_b32_e32 v139, 8, v139
	v_lshl_add_u64 v[146:147], v[152:153], 0, v[146:147]
	v_lshlrev_b32_e32 v154, 2, v145
	v_mov_b32_e32 v155, v193
	v_and_b32_e32 v139, 0x30000, v139
	v_lshl_add_u64 v[146:147], v[146:147], 0, v[154:155]
	v_or_b32_e32 v158, s30, v139
	v_mov_b32_e32 v159, s31
	v_mov_b32_e32 v184, v128
	v_mov_b32_e32 v185, v129
	v_mov_b32_e32 v186, v130
	v_mov_b32_e32 v187, v131
	v_mov_b32_e32 v188, v132
	v_mov_b32_e32 v189, v133
	v_mov_b32_e32 v190, v134
	v_mov_b32_e32 v191, v135
	s_nop 1
	v_permlane16_swap_b32_e32 v184, v188
	v_permlane16_swap_b32_e32 v185, v189
	v_permlane16_swap_b32_e32 v186, v190
	v_permlane16_swap_b32_e32 v187, v191
	s_nop 1
	v_permlane32_swap_b32_e32 v184, v188
	v_permlane32_swap_b32_e32 v185, v189
	v_permlane32_swap_b32_e32 v186, v190
	v_permlane32_swap_b32_e32 v187, v191
	v_lshl_add_u64 v[182:183], v[146:147], 0, v[178:179]
	global_store_dwordx4 v[182:183], v[184:187], off
	global_store_dwordx4 v[182:183], v[188:191], off offset:64
	v_lshlrev_b32_sdwa v146, v240, v137 dst_sel:DWORD dst_unused:UNUSED_PAD src0_sel:DWORD src1_sel:BYTE_0
	v_lshl_add_u64 v[148:149], v[158:159], 1, s[96:97]
	s_and_saveexec_b64 s[4:5], s[0:1]
	s_xor_b64 s[4:5], exec, s[4:5]
	s_cbranch_execz .LBB0_1095
	v_mov_b32_e32 v147, v193
	v_lshl_add_u64 v[156:157], v[148:149], 0, v[146:147]
	v_lshl_add_u64 v[156:157], v[172:173], 1, v[156:157]
	v_cvt_pk_bf16_f32 v128, v128, s0
	global_store_short v[156:157], v128, off
	v_cvt_pk_bf16_f32 v128, v132, s0
	global_store_short v[156:157], v128, off offset:2048
	v_cvt_pk_bf16_f32 v128, v129, s0
	global_store_short v[156:157], v128, off offset:512
	v_cvt_pk_bf16_f32 v128, v133, s0
	global_store_short v[156:157], v128, off offset:2560
	v_cvt_pk_bf16_f32 v128, v130, s0
	global_store_short v[156:157], v128, off offset:1024
	v_cvt_pk_bf16_f32 v128, v134, s0
	global_store_short v[156:157], v128, off offset:3072
	v_cvt_pk_bf16_f32 v128, v131, s0
	global_store_short v[156:157], v128, off offset:1536
	v_cvt_pk_bf16_f32 v128, v135, s0
	global_store_short v[156:157], v128, off offset:3584

.LBB0_1097:
	s_or_b64 exec, exec, s[4:5]
	v_add_u32_e32 v164, 16, v172
	v_add_u32_e32 v128, s63, v164
	v_ashrrev_i32_e32 v129, 31, v128
	v_lshl_add_u64 v[130:131], v[128:129], 2, s[90:91]
	global_load_dword v130, v[130:131], off
	v_lshlrev_b64 v[160:161], 12, v[128:129]
	v_mov_b32_e32 v139, v193
	v_lshl_add_u64 v[128:129], v[142:143], 0, v[160:161]
	v_lshl_add_u64 v[166:167], v[128:129], 0, v[138:139]
	s_waitcnt vmcnt(0) lgkmcnt(0)
	v_fmamk_f32 v130, v130, 0x3a800000, v215
	v_rsq_f32_e32 v162, v130
	s_nop 0
	v_pk_mul_f32 v[134:135], v[118:119], v[162:163] op_sel_hi:[1,0]
	v_pk_mul_f32 v[132:133], v[116:117], v[162:163] op_sel_hi:[1,0]
	v_pk_mul_f32 v[130:131], v[114:115], v[162:163] op_sel_hi:[1,0]
	v_pk_mul_f32 v[128:129], v[112:113], v[162:163] op_sel_hi:[1,0]
	v_mov_b32_e32 v184, v132
	v_mov_b32_e32 v185, v133
	v_mov_b32_e32 v186, v134
	v_mov_b32_e32 v187, v135
	v_mov_b32_e32 v188, v128
	v_mov_b32_e32 v189, v129
	v_mov_b32_e32 v190, v130
	v_mov_b32_e32 v191, v131
	s_nop 1
	v_permlane16_swap_b32_e32 v184, v188
	v_permlane16_swap_b32_e32 v185, v189
	v_permlane16_swap_b32_e32 v186, v190
	v_permlane16_swap_b32_e32 v187, v191
	s_nop 1
	v_permlane32_swap_b32_e32 v184, v188
	v_permlane32_swap_b32_e32 v185, v189
	v_permlane32_swap_b32_e32 v186, v190
	v_permlane32_swap_b32_e32 v187, v191
	v_lshl_add_u64 v[182:183], v[166:167], 0, v[178:179]
	global_store_dwordx4 v[182:183], v[184:187], off
	global_store_dwordx4 v[182:183], v[188:191], off offset:64
	s_and_saveexec_b64 s[4:5], vcc
	s_xor_b64 s[4:5], exec, s[4:5]
	s_cbranch_execz .LBB0_1099
	v_mov_b32_e32 v137, v193
	v_lshl_add_u64 v[166:167], v[140:141], 0, v[136:137]
	v_lshl_add_u64 v[166:167], v[172:173], 1, v[166:167]
	v_cvt_pk_bf16_f32 v128, v128, s0
	global_store_short v[166:167], v128, off offset:2080
	v_cvt_pk_bf16_f32 v128, v133, s0
	global_store_short v[166:167], v128, off offset:544
	v_cvt_pk_bf16_f32 v128, v129, s0
	global_store_short v[166:167], v128, off offset:2592
	v_cvt_pk_bf16_f32 v128, v134, s0
	global_store_short v[166:167], v128, off offset:1056
	v_cvt_pk_bf16_f32 v128, v130, s0
	global_store_short v[166:167], v128, off offset:3104
	v_cvt_pk_bf16_f32 v128, v135, s0
	v_cvt_pk_bf16_f32 v132, v132, s0
	global_store_short v[166:167], v128, off offset:1568
	v_cvt_pk_bf16_f32 v128, v131, s0
	global_store_short v[166:167], v132, off offset:32
	global_store_short v[166:167], v128, off offset:3616

.LBB0_1101:
	s_or_b64 exec, exec, s[4:5]
	v_mov_b32_e32 v163, v162
	v_mov_b32_e32 v132, v162
	v_mov_b32_e32 v133, v162
	v_lshl_add_u64 v[160:161], v[152:153], 0, v[160:161]
	v_mov_b32_e32 v155, v193
	v_pk_mul_f32 v[130:131], v[86:87], v[132:133]
	v_pk_mul_f32 v[128:129], v[84:85], v[162:163]
	v_pk_mul_f32 v[134:135], v[82:83], v[132:133]
	v_pk_mul_f32 v[132:133], v[80:81], v[162:163]
	v_lshl_add_u64 v[160:161], v[160:161], 0, v[154:155]
	v_mov_b32_e32 v184, v128
	v_mov_b32_e32 v185, v129
	v_mov_b32_e32 v186, v130
	v_mov_b32_e32 v187, v131
	v_mov_b32_e32 v188, v132
	v_mov_b32_e32 v189, v133
	v_mov_b32_e32 v190, v134
	v_mov_b32_e32 v191, v135
	s_nop 1
	v_permlane16_swap_b32_e32 v184, v188
	v_permlane16_swap_b32_e32 v185, v189
	v_permlane16_swap_b32_e32 v186, v190
	v_permlane16_swap_b32_e32 v187, v191
	s_nop 1
	v_permlane32_swap_b32_e32 v184, v188
	v_permlane32_swap_b32_e32 v185, v189
	v_permlane32_swap_b32_e32 v186, v190
	v_permlane32_swap_b32_e32 v187, v191
	v_lshl_add_u64 v[182:183], v[160:161], 0, v[178:179]
	global_store_dwordx4 v[182:183], v[184:187], off
	global_store_dwordx4 v[182:183], v[188:191], off offset:64
	s_and_saveexec_b64 s[4:5], s[0:1]
	s_xor_b64 s[4:5], exec, s[4:5]
	s_cbranch_execz .LBB0_1103
	v_mov_b32_e32 v147, v193
	v_lshl_add_u64 v[160:161], v[148:149], 0, v[146:147]
	v_lshl_add_u64 v[160:161], v[172:173], 1, v[160:161]
	v_cvt_pk_bf16_f32 v128, v128, s0
	global_store_short v[160:161], v128, off offset:32
	v_cvt_pk_bf16_f32 v128, v132, s0
	global_store_short v[160:161], v128, off offset:2080
	v_cvt_pk_bf16_f32 v128, v129, s0
	global_store_short v[160:161], v128, off offset:544
	v_cvt_pk_bf16_f32 v128, v133, s0
	global_store_short v[160:161], v128, off offset:2592
	v_cvt_pk_bf16_f32 v128, v130, s0
	global_store_short v[160:161], v128, off offset:1056
	v_cvt_pk_bf16_f32 v128, v134, s0
	global_store_short v[160:161], v128, off offset:3104
	v_cvt_pk_bf16_f32 v128, v131, s0
	global_store_short v[160:161], v128, off offset:1568
	v_cvt_pk_bf16_f32 v128, v135, s0
	global_store_short v[160:161], v128, off offset:3616

.LBB0_1105:
	s_or_b64 exec, exec, s[4:5]
	v_add_u32_e32 v164, 32, v172
	v_add_u32_e32 v128, s63, v164
	v_ashrrev_i32_e32 v129, 31, v128
	v_lshl_add_u64 v[130:131], v[128:129], 2, s[90:91]
	global_load_dword v130, v[130:131], off
	v_lshlrev_b64 v[160:161], 12, v[128:129]
	v_mov_b32_e32 v139, v193
	v_lshl_add_u64 v[128:129], v[142:143], 0, v[160:161]
	v_lshl_add_u64 v[166:167], v[128:129], 0, v[138:139]
	s_waitcnt vmcnt(0) lgkmcnt(0)
	v_fmamk_f32 v130, v130, 0x3a800000, v215
	v_rsq_f32_e32 v162, v130
	s_nop 0
	v_pk_mul_f32 v[134:135], v[110:111], v[162:163] op_sel_hi:[1,0]
	v_pk_mul_f32 v[132:133], v[108:109], v[162:163] op_sel_hi:[1,0]
	v_pk_mul_f32 v[130:131], v[106:107], v[162:163] op_sel_hi:[1,0]
	v_pk_mul_f32 v[128:129], v[104:105], v[162:163] op_sel_hi:[1,0]
	v_mov_b32_e32 v184, v132
	v_mov_b32_e32 v185, v133
	v_mov_b32_e32 v186, v134
	v_mov_b32_e32 v187, v135
	v_mov_b32_e32 v188, v128
	v_mov_b32_e32 v189, v129
	v_mov_b32_e32 v190, v130
	v_mov_b32_e32 v191, v131
	s_nop 1
	v_permlane16_swap_b32_e32 v184, v188
	v_permlane16_swap_b32_e32 v185, v189
	v_permlane16_swap_b32_e32 v186, v190
	v_permlane16_swap_b32_e32 v187, v191
	s_nop 1
	v_permlane32_swap_b32_e32 v184, v188
	v_permlane32_swap_b32_e32 v185, v189
	v_permlane32_swap_b32_e32 v186, v190
	v_permlane32_swap_b32_e32 v187, v191
	v_lshl_add_u64 v[182:183], v[166:167], 0, v[178:179]
	global_store_dwordx4 v[182:183], v[184:187], off
	global_store_dwordx4 v[182:183], v[188:191], off offset:64
	s_and_saveexec_b64 s[4:5], vcc
	s_xor_b64 s[4:5], exec, s[4:5]
	s_cbranch_execz .LBB0_1107
	v_mov_b32_e32 v137, v193
	v_lshl_add_u64 v[166:167], v[140:141], 0, v[136:137]
	v_lshl_add_u64 v[166:167], v[172:173], 1, v[166:167]
	v_cvt_pk_bf16_f32 v128, v128, s0
	global_store_short v[166:167], v128, off offset:2112
	v_cvt_pk_bf16_f32 v128, v133, s0
	global_store_short v[166:167], v128, off offset:576
	v_cvt_pk_bf16_f32 v128, v129, s0
	global_store_short v[166:167], v128, off offset:2624
	v_cvt_pk_bf16_f32 v128, v134, s0
	global_store_short v[166:167], v128, off offset:1088
	v_cvt_pk_bf16_f32 v128, v130, s0
	global_store_short v[166:167], v128, off offset:3136
	v_cvt_pk_bf16_f32 v128, v135, s0
	v_cvt_pk_bf16_f32 v132, v132, s0
	global_store_short v[166:167], v128, off offset:1600
	v_cvt_pk_bf16_f32 v128, v131, s0
	global_store_short v[166:167], v132, off offset:64
	global_store_short v[166:167], v128, off offset:3648

.LBB0_1109:
	s_or_b64 exec, exec, s[4:5]
	v_mov_b32_e32 v163, v162
	v_mov_b32_e32 v132, v162
	v_mov_b32_e32 v133, v162
	v_lshl_add_u64 v[160:161], v[152:153], 0, v[160:161]
	v_mov_b32_e32 v155, v193
	v_pk_mul_f32 v[130:131], v[78:79], v[132:133]
	v_pk_mul_f32 v[128:129], v[76:77], v[162:163]
	v_pk_mul_f32 v[134:135], v[74:75], v[132:133]
	v_pk_mul_f32 v[132:133], v[72:73], v[162:163]
	v_lshl_add_u64 v[160:161], v[160:161], 0, v[154:155]
	v_mov_b32_e32 v184, v128
	v_mov_b32_e32 v185, v129
	v_mov_b32_e32 v186, v130
	v_mov_b32_e32 v187, v131
	v_mov_b32_e32 v188, v132
	v_mov_b32_e32 v189, v133
	v_mov_b32_e32 v190, v134
	v_mov_b32_e32 v191, v135
	s_nop 1
	v_permlane16_swap_b32_e32 v184, v188
	v_permlane16_swap_b32_e32 v185, v189
	v_permlane16_swap_b32_e32 v186, v190
	v_permlane16_swap_b32_e32 v187, v191
	s_nop 1
	v_permlane32_swap_b32_e32 v184, v188
	v_permlane32_swap_b32_e32 v185, v189
	v_permlane32_swap_b32_e32 v186, v190
	v_permlane32_swap_b32_e32 v187, v191
	v_lshl_add_u64 v[182:183], v[160:161], 0, v[178:179]
	global_store_dwordx4 v[182:183], v[184:187], off
	global_store_dwordx4 v[182:183], v[188:191], off offset:64
	s_and_saveexec_b64 s[4:5], s[0:1]
	s_xor_b64 s[4:5], exec, s[4:5]
	s_cbranch_execz .LBB0_1111
	v_mov_b32_e32 v147, v193
	v_lshl_add_u64 v[160:161], v[148:149], 0, v[146:147]
	v_lshl_add_u64 v[160:161], v[172:173], 1, v[160:161]
	v_cvt_pk_bf16_f32 v128, v128, s0
	global_store_short v[160:161], v128, off offset:64
	v_cvt_pk_bf16_f32 v128, v132, s0
	global_store_short v[160:161], v128, off offset:2112
	v_cvt_pk_bf16_f32 v128, v129, s0
	global_store_short v[160:161], v128, off offset:576
	v_cvt_pk_bf16_f32 v128, v133, s0
	global_store_short v[160:161], v128, off offset:2624
	v_cvt_pk_bf16_f32 v128, v130, s0
	global_store_short v[160:161], v128, off offset:1088
	v_cvt_pk_bf16_f32 v128, v134, s0
	global_store_short v[160:161], v128, off offset:3136
	v_cvt_pk_bf16_f32 v128, v131, s0
	global_store_short v[160:161], v128, off offset:1600
	v_cvt_pk_bf16_f32 v128, v135, s0
	global_store_short v[160:161], v128, off offset:3648

.LBB0_1113:
	s_or_b64 exec, exec, s[4:5]
	v_add_u32_e32 v164, 48, v172
	v_add_u32_e32 v128, s63, v164
	v_ashrrev_i32_e32 v129, 31, v128
	v_lshl_add_u64 v[130:131], v[128:129], 2, s[90:91]
	global_load_dword v130, v[130:131], off
	v_lshlrev_b64 v[160:161], 12, v[128:129]
	v_mov_b32_e32 v139, v193
	v_lshl_add_u64 v[128:129], v[142:143], 0, v[160:161]
	v_lshl_add_u64 v[166:167], v[128:129], 0, v[138:139]
	s_waitcnt vmcnt(0) lgkmcnt(0)
	v_fmamk_f32 v130, v130, 0x3a800000, v215
	v_rsq_f32_e32 v162, v130
	s_nop 0
	v_pk_mul_f32 v[134:135], v[102:103], v[162:163] op_sel_hi:[1,0]
	v_pk_mul_f32 v[132:133], v[100:101], v[162:163] op_sel_hi:[1,0]
	v_pk_mul_f32 v[130:131], v[98:99], v[162:163] op_sel_hi:[1,0]
	v_pk_mul_f32 v[128:129], v[96:97], v[162:163] op_sel_hi:[1,0]
	v_mov_b32_e32 v184, v132
	v_mov_b32_e32 v185, v133
	v_mov_b32_e32 v186, v134
	v_mov_b32_e32 v187, v135
	v_mov_b32_e32 v188, v128
	v_mov_b32_e32 v189, v129
	v_mov_b32_e32 v190, v130
	v_mov_b32_e32 v191, v131
	s_nop 1
	v_permlane16_swap_b32_e32 v184, v188
	v_permlane16_swap_b32_e32 v185, v189
	v_permlane16_swap_b32_e32 v186, v190
	v_permlane16_swap_b32_e32 v187, v191
	s_nop 1
	v_permlane32_swap_b32_e32 v184, v188
	v_permlane32_swap_b32_e32 v185, v189
	v_permlane32_swap_b32_e32 v186, v190
	v_permlane32_swap_b32_e32 v187, v191
	v_lshl_add_u64 v[182:183], v[166:167], 0, v[178:179]
	global_store_dwordx4 v[182:183], v[184:187], off
	global_store_dwordx4 v[182:183], v[188:191], off offset:64
	s_and_saveexec_b64 s[4:5], vcc
	s_xor_b64 s[4:5], exec, s[4:5]
	s_cbranch_execz .LBB0_1115
	v_mov_b32_e32 v137, v193
	v_lshl_add_u64 v[166:167], v[140:141], 0, v[136:137]
	v_lshl_add_u64 v[166:167], v[172:173], 1, v[166:167]
	v_cvt_pk_bf16_f32 v128, v128, s0
	global_store_short v[166:167], v128, off offset:2144
	v_cvt_pk_bf16_f32 v128, v133, s0
	global_store_short v[166:167], v128, off offset:608
	v_cvt_pk_bf16_f32 v128, v129, s0
	global_store_short v[166:167], v128, off offset:2656
	v_cvt_pk_bf16_f32 v128, v134, s0
	global_store_short v[166:167], v128, off offset:1120
	v_cvt_pk_bf16_f32 v128, v130, s0
	global_store_short v[166:167], v128, off offset:3168
	v_cvt_pk_bf16_f32 v128, v135, s0
	v_cvt_pk_bf16_f32 v132, v132, s0
	global_store_short v[166:167], v128, off offset:1632
	v_cvt_pk_bf16_f32 v128, v131, s0
	global_store_short v[166:167], v132, off offset:96
	global_store_short v[166:167], v128, off offset:3680

.LBB0_1117:
	s_or_b64 exec, exec, s[4:5]
	v_mov_b32_e32 v163, v162
	v_mov_b32_e32 v132, v162
	v_mov_b32_e32 v133, v162
	v_lshl_add_u64 v[160:161], v[152:153], 0, v[160:161]
	v_mov_b32_e32 v155, v193
	v_pk_mul_f32 v[130:131], v[70:71], v[132:133]
	v_pk_mul_f32 v[128:129], v[68:69], v[162:163]
	v_pk_mul_f32 v[134:135], v[66:67], v[132:133]
	v_pk_mul_f32 v[132:133], v[64:65], v[162:163]
	v_lshl_add_u64 v[160:161], v[160:161], 0, v[154:155]
	v_mov_b32_e32 v184, v128
	v_mov_b32_e32 v185, v129
	v_mov_b32_e32 v186, v130
	v_mov_b32_e32 v187, v131
	v_mov_b32_e32 v188, v132
	v_mov_b32_e32 v189, v133
	v_mov_b32_e32 v190, v134
	v_mov_b32_e32 v191, v135
	s_nop 1
	v_permlane16_swap_b32_e32 v184, v188
	v_permlane16_swap_b32_e32 v185, v189
	v_permlane16_swap_b32_e32 v186, v190
	v_permlane16_swap_b32_e32 v187, v191
	s_nop 1
	v_permlane32_swap_b32_e32 v184, v188
	v_permlane32_swap_b32_e32 v185, v189
	v_permlane32_swap_b32_e32 v186, v190
	v_permlane32_swap_b32_e32 v187, v191
	v_lshl_add_u64 v[182:183], v[160:161], 0, v[178:179]
	global_store_dwordx4 v[182:183], v[184:187], off
	global_store_dwordx4 v[182:183], v[188:191], off offset:64
	s_and_saveexec_b64 s[4:5], s[0:1]
	s_xor_b64 s[4:5], exec, s[4:5]
	s_cbranch_execz .LBB0_1119
	v_mov_b32_e32 v147, v193
	v_lshl_add_u64 v[160:161], v[148:149], 0, v[146:147]
	v_lshl_add_u64 v[160:161], v[172:173], 1, v[160:161]
	v_cvt_pk_bf16_f32 v128, v128, s0
	global_store_short v[160:161], v128, off offset:96
	v_cvt_pk_bf16_f32 v128, v132, s0
	global_store_short v[160:161], v128, off offset:2144
	v_cvt_pk_bf16_f32 v128, v129, s0
	global_store_short v[160:161], v128, off offset:608
	v_cvt_pk_bf16_f32 v128, v133, s0
	global_store_short v[160:161], v128, off offset:2656
	v_cvt_pk_bf16_f32 v128, v130, s0
	global_store_short v[160:161], v128, off offset:1120
	v_cvt_pk_bf16_f32 v128, v134, s0
	global_store_short v[160:161], v128, off offset:3168
	v_cvt_pk_bf16_f32 v128, v131, s0
	global_store_short v[160:161], v128, off offset:1632
	v_cvt_pk_bf16_f32 v128, v135, s0
	global_store_short v[160:161], v128, off offset:3680

.LBB0_1121:
	s_or_b64 exec, exec, s[4:5]
	v_add_u32_e32 v164, 0x80, v172
	v_add_u32_e32 v128, s63, v164
	v_ashrrev_i32_e32 v129, 31, v128
	v_lshl_add_u64 v[130:131], v[128:129], 2, s[90:91]
	global_load_dword v130, v[130:131], off
	v_lshlrev_b64 v[160:161], 12, v[128:129]
	v_mov_b32_e32 v139, v193
	v_lshl_add_u64 v[128:129], v[142:143], 0, v[160:161]
	v_lshl_add_u64 v[166:167], v[128:129], 0, v[138:139]
	s_waitcnt vmcnt(0) lgkmcnt(0)
	v_fmamk_f32 v130, v130, 0x3a800000, v215
	v_rsq_f32_e32 v162, v130
	s_nop 0
	v_pk_mul_f32 v[134:135], v[62:63], v[162:163] op_sel_hi:[1,0]
	v_pk_mul_f32 v[132:133], v[60:61], v[162:163] op_sel_hi:[1,0]
	v_pk_mul_f32 v[130:131], v[58:59], v[162:163] op_sel_hi:[1,0]
	v_pk_mul_f32 v[128:129], v[56:57], v[162:163] op_sel_hi:[1,0]
	v_mov_b32_e32 v184, v132
	v_mov_b32_e32 v185, v133
	v_mov_b32_e32 v186, v134
	v_mov_b32_e32 v187, v135
	v_mov_b32_e32 v188, v128
	v_mov_b32_e32 v189, v129
	v_mov_b32_e32 v190, v130
	v_mov_b32_e32 v191, v131
	s_nop 1
	v_permlane16_swap_b32_e32 v184, v188
	v_permlane16_swap_b32_e32 v185, v189
	v_permlane16_swap_b32_e32 v186, v190
	v_permlane16_swap_b32_e32 v187, v191
	s_nop 1
	v_permlane32_swap_b32_e32 v184, v188
	v_permlane32_swap_b32_e32 v185, v189
	v_permlane32_swap_b32_e32 v186, v190
	v_permlane32_swap_b32_e32 v187, v191
	v_lshl_add_u64 v[182:183], v[166:167], 0, v[178:179]
	global_store_dwordx4 v[182:183], v[184:187], off
	global_store_dwordx4 v[182:183], v[188:191], off offset:64
	s_and_saveexec_b64 s[4:5], vcc
	s_xor_b64 s[4:5], exec, s[4:5]
	s_cbranch_execz .LBB0_1123
	v_mov_b32_e32 v137, v193
	v_lshl_add_u64 v[166:167], v[140:141], 0, v[136:137]
	v_lshl_add_u64 v[166:167], v[172:173], 1, v[166:167]
	v_cvt_pk_bf16_f32 v128, v128, s0
	global_store_short v[166:167], v128, off offset:2304
	v_cvt_pk_bf16_f32 v128, v133, s0
	global_store_short v[166:167], v128, off offset:768
	v_cvt_pk_bf16_f32 v128, v129, s0
	global_store_short v[166:167], v128, off offset:2816
	v_cvt_pk_bf16_f32 v128, v134, s0
	global_store_short v[166:167], v128, off offset:1280
	v_cvt_pk_bf16_f32 v128, v130, s0
	global_store_short v[166:167], v128, off offset:3328
	v_cvt_pk_bf16_f32 v128, v135, s0
	v_cvt_pk_bf16_f32 v132, v132, s0
	global_store_short v[166:167], v128, off offset:1792
	v_cvt_pk_bf16_f32 v128, v131, s0
	global_store_short v[166:167], v132, off offset:256
	global_store_short v[166:167], v128, off offset:3840

.LBB0_1125:
	s_or_b64 exec, exec, s[4:5]
	v_mov_b32_e32 v163, v162
	v_mov_b32_e32 v132, v162
	v_mov_b32_e32 v133, v162
	v_lshl_add_u64 v[160:161], v[152:153], 0, v[160:161]
	v_mov_b32_e32 v155, v193
	v_pk_mul_f32 v[130:131], v[30:31], v[132:133]
	v_pk_mul_f32 v[128:129], v[28:29], v[162:163]
	v_pk_mul_f32 v[134:135], v[26:27], v[132:133]
	v_pk_mul_f32 v[132:133], v[24:25], v[162:163]
	v_lshl_add_u64 v[160:161], v[160:161], 0, v[154:155]
	v_mov_b32_e32 v184, v128
	v_mov_b32_e32 v185, v129
	v_mov_b32_e32 v186, v130
	v_mov_b32_e32 v187, v131
	v_mov_b32_e32 v188, v132
	v_mov_b32_e32 v189, v133
	v_mov_b32_e32 v190, v134
	v_mov_b32_e32 v191, v135
	s_nop 1
	v_permlane16_swap_b32_e32 v184, v188
	v_permlane16_swap_b32_e32 v185, v189
	v_permlane16_swap_b32_e32 v186, v190
	v_permlane16_swap_b32_e32 v187, v191
	s_nop 1
	v_permlane32_swap_b32_e32 v184, v188
	v_permlane32_swap_b32_e32 v185, v189
	v_permlane32_swap_b32_e32 v186, v190
	v_permlane32_swap_b32_e32 v187, v191
	v_lshl_add_u64 v[182:183], v[160:161], 0, v[178:179]
	global_store_dwordx4 v[182:183], v[184:187], off
	global_store_dwordx4 v[182:183], v[188:191], off offset:64
	s_and_saveexec_b64 s[4:5], s[0:1]
	s_xor_b64 s[4:5], exec, s[4:5]
	s_cbranch_execz .LBB0_1127
	v_mov_b32_e32 v147, v193
	v_lshl_add_u64 v[160:161], v[148:149], 0, v[146:147]
	v_lshl_add_u64 v[160:161], v[172:173], 1, v[160:161]
	v_cvt_pk_bf16_f32 v128, v128, s0
	global_store_short v[160:161], v128, off offset:256
	v_cvt_pk_bf16_f32 v128, v132, s0
	global_store_short v[160:161], v128, off offset:2304
	v_cvt_pk_bf16_f32 v128, v129, s0
	global_store_short v[160:161], v128, off offset:768
	v_cvt_pk_bf16_f32 v128, v133, s0
	global_store_short v[160:161], v128, off offset:2816
	v_cvt_pk_bf16_f32 v128, v130, s0
	global_store_short v[160:161], v128, off offset:1280
	v_cvt_pk_bf16_f32 v128, v134, s0
	global_store_short v[160:161], v128, off offset:3328
	v_cvt_pk_bf16_f32 v128, v131, s0
	global_store_short v[160:161], v128, off offset:1792
	v_cvt_pk_bf16_f32 v128, v135, s0
	global_store_short v[160:161], v128, off offset:3840

.LBB0_1129:
	s_or_b64 exec, exec, s[4:5]
	v_add_u32_e32 v164, 0x90, v172
	v_add_u32_e32 v128, s63, v164
	v_ashrrev_i32_e32 v129, 31, v128
	v_lshl_add_u64 v[130:131], v[128:129], 2, s[90:91]
	global_load_dword v130, v[130:131], off
	v_lshlrev_b64 v[160:161], 12, v[128:129]
	v_mov_b32_e32 v139, v193
	v_lshl_add_u64 v[128:129], v[142:143], 0, v[160:161]
	v_lshl_add_u64 v[166:167], v[128:129], 0, v[138:139]
	s_waitcnt vmcnt(0) lgkmcnt(0)
	v_fmamk_f32 v130, v130, 0x3a800000, v215
	v_rsq_f32_e32 v162, v130
	s_nop 0
	v_pk_mul_f32 v[134:135], v[54:55], v[162:163] op_sel_hi:[1,0]
	v_pk_mul_f32 v[132:133], v[52:53], v[162:163] op_sel_hi:[1,0]
	v_pk_mul_f32 v[130:131], v[50:51], v[162:163] op_sel_hi:[1,0]
	v_pk_mul_f32 v[128:129], v[48:49], v[162:163] op_sel_hi:[1,0]
	v_mov_b32_e32 v184, v132
	v_mov_b32_e32 v185, v133
	v_mov_b32_e32 v186, v134
	v_mov_b32_e32 v187, v135
	v_mov_b32_e32 v188, v128
	v_mov_b32_e32 v189, v129
	v_mov_b32_e32 v190, v130
	v_mov_b32_e32 v191, v131
	s_nop 1
	v_permlane16_swap_b32_e32 v184, v188
	v_permlane16_swap_b32_e32 v185, v189
	v_permlane16_swap_b32_e32 v186, v190
	v_permlane16_swap_b32_e32 v187, v191
	s_nop 1
	v_permlane32_swap_b32_e32 v184, v188
	v_permlane32_swap_b32_e32 v185, v189
	v_permlane32_swap_b32_e32 v186, v190
	v_permlane32_swap_b32_e32 v187, v191
	v_lshl_add_u64 v[182:183], v[166:167], 0, v[178:179]
	global_store_dwordx4 v[182:183], v[184:187], off
	global_store_dwordx4 v[182:183], v[188:191], off offset:64
	s_and_saveexec_b64 s[4:5], vcc
	s_xor_b64 s[4:5], exec, s[4:5]
	s_cbranch_execz .LBB0_1131
	v_mov_b32_e32 v137, v193
	v_lshl_add_u64 v[166:167], v[140:141], 0, v[136:137]
	v_lshl_add_u64 v[166:167], v[172:173], 1, v[166:167]
	v_cvt_pk_bf16_f32 v128, v128, s0
	global_store_short v[166:167], v128, off offset:2336
	v_cvt_pk_bf16_f32 v128, v133, s0
	global_store_short v[166:167], v128, off offset:800
	v_cvt_pk_bf16_f32 v128, v129, s0
	global_store_short v[166:167], v128, off offset:2848
	v_cvt_pk_bf16_f32 v128, v134, s0
	global_store_short v[166:167], v128, off offset:1312
	v_cvt_pk_bf16_f32 v128, v130, s0
	global_store_short v[166:167], v128, off offset:3360
	v_cvt_pk_bf16_f32 v128, v135, s0
	v_cvt_pk_bf16_f32 v132, v132, s0
	global_store_short v[166:167], v128, off offset:1824
	v_cvt_pk_bf16_f32 v128, v131, s0
	global_store_short v[166:167], v132, off offset:288
	global_store_short v[166:167], v128, off offset:3872

.LBB0_1133:
	s_or_b64 exec, exec, s[4:5]
	v_mov_b32_e32 v163, v162
	v_mov_b32_e32 v132, v162
	v_mov_b32_e32 v133, v162
	v_lshl_add_u64 v[160:161], v[152:153], 0, v[160:161]
	v_mov_b32_e32 v155, v193
	v_pk_mul_f32 v[130:131], v[22:23], v[132:133]
	v_pk_mul_f32 v[128:129], v[20:21], v[162:163]
	v_pk_mul_f32 v[134:135], v[18:19], v[132:133]
	v_pk_mul_f32 v[132:133], v[16:17], v[162:163]
	v_lshl_add_u64 v[160:161], v[160:161], 0, v[154:155]
	v_mov_b32_e32 v184, v128
	v_mov_b32_e32 v185, v129
	v_mov_b32_e32 v186, v130
	v_mov_b32_e32 v187, v131
	v_mov_b32_e32 v188, v132
	v_mov_b32_e32 v189, v133
	v_mov_b32_e32 v190, v134
	v_mov_b32_e32 v191, v135
	s_nop 1
	v_permlane16_swap_b32_e32 v184, v188
	v_permlane16_swap_b32_e32 v185, v189
	v_permlane16_swap_b32_e32 v186, v190
	v_permlane16_swap_b32_e32 v187, v191
	s_nop 1
	v_permlane32_swap_b32_e32 v184, v188
	v_permlane32_swap_b32_e32 v185, v189
	v_permlane32_swap_b32_e32 v186, v190
	v_permlane32_swap_b32_e32 v187, v191
	v_lshl_add_u64 v[182:183], v[160:161], 0, v[178:179]
	global_store_dwordx4 v[182:183], v[184:187], off
	global_store_dwordx4 v[182:183], v[188:191], off offset:64
	s_and_saveexec_b64 s[4:5], s[0:1]
	s_xor_b64 s[4:5], exec, s[4:5]
	s_cbranch_execz .LBB0_1135
	v_mov_b32_e32 v147, v193
	v_lshl_add_u64 v[160:161], v[148:149], 0, v[146:147]
	v_lshl_add_u64 v[160:161], v[172:173], 1, v[160:161]
	v_cvt_pk_bf16_f32 v128, v128, s0
	global_store_short v[160:161], v128, off offset:288
	v_cvt_pk_bf16_f32 v128, v132, s0
	global_store_short v[160:161], v128, off offset:2336
	v_cvt_pk_bf16_f32 v128, v129, s0
	global_store_short v[160:161], v128, off offset:800
	v_cvt_pk_bf16_f32 v128, v133, s0
	global_store_short v[160:161], v128, off offset:2848
	v_cvt_pk_bf16_f32 v128, v130, s0
	global_store_short v[160:161], v128, off offset:1312
	v_cvt_pk_bf16_f32 v128, v134, s0
	global_store_short v[160:161], v128, off offset:3360
	v_cvt_pk_bf16_f32 v128, v131, s0
	global_store_short v[160:161], v128, off offset:1824
	v_cvt_pk_bf16_f32 v128, v135, s0
	global_store_short v[160:161], v128, off offset:3872

.LBB0_1137:
	s_or_b64 exec, exec, s[4:5]
	v_add_u32_e32 v164, 0xa0, v172
	v_add_u32_e32 v128, s63, v164
	v_ashrrev_i32_e32 v129, 31, v128
	v_lshl_add_u64 v[130:131], v[128:129], 2, s[90:91]
	global_load_dword v130, v[130:131], off
	v_lshlrev_b64 v[160:161], 12, v[128:129]
	v_mov_b32_e32 v139, v193
	v_lshl_add_u64 v[128:129], v[142:143], 0, v[160:161]
	v_lshl_add_u64 v[166:167], v[128:129], 0, v[138:139]
	s_waitcnt vmcnt(0) lgkmcnt(0)
	v_fmamk_f32 v130, v130, 0x3a800000, v215
	v_rsq_f32_e32 v162, v130
	s_nop 0
	v_pk_mul_f32 v[134:135], v[46:47], v[162:163] op_sel_hi:[1,0]
	v_pk_mul_f32 v[132:133], v[44:45], v[162:163] op_sel_hi:[1,0]
	v_pk_mul_f32 v[130:131], v[42:43], v[162:163] op_sel_hi:[1,0]
	v_pk_mul_f32 v[128:129], v[40:41], v[162:163] op_sel_hi:[1,0]
	v_mov_b32_e32 v184, v132
	v_mov_b32_e32 v185, v133
	v_mov_b32_e32 v186, v134
	v_mov_b32_e32 v187, v135
	v_mov_b32_e32 v188, v128
	v_mov_b32_e32 v189, v129
	v_mov_b32_e32 v190, v130
	v_mov_b32_e32 v191, v131
	s_nop 1
	v_permlane16_swap_b32_e32 v184, v188
	v_permlane16_swap_b32_e32 v185, v189
	v_permlane16_swap_b32_e32 v186, v190
	v_permlane16_swap_b32_e32 v187, v191
	s_nop 1
	v_permlane32_swap_b32_e32 v184, v188
	v_permlane32_swap_b32_e32 v185, v189
	v_permlane32_swap_b32_e32 v186, v190
	v_permlane32_swap_b32_e32 v187, v191
	v_lshl_add_u64 v[182:183], v[166:167], 0, v[178:179]
	global_store_dwordx4 v[182:183], v[184:187], off
	global_store_dwordx4 v[182:183], v[188:191], off offset:64
	s_and_saveexec_b64 s[4:5], vcc
	s_xor_b64 s[4:5], exec, s[4:5]
	s_cbranch_execz .LBB0_1139
	v_mov_b32_e32 v137, v193
	v_lshl_add_u64 v[166:167], v[140:141], 0, v[136:137]
	v_lshl_add_u64 v[166:167], v[172:173], 1, v[166:167]
	v_cvt_pk_bf16_f32 v128, v128, s0
	global_store_short v[166:167], v128, off offset:2368
	v_cvt_pk_bf16_f32 v128, v133, s0
	global_store_short v[166:167], v128, off offset:832
	v_cvt_pk_bf16_f32 v128, v129, s0
	global_store_short v[166:167], v128, off offset:2880
	v_cvt_pk_bf16_f32 v128, v134, s0
	global_store_short v[166:167], v128, off offset:1344
	v_cvt_pk_bf16_f32 v128, v130, s0
	global_store_short v[166:167], v128, off offset:3392
	v_cvt_pk_bf16_f32 v128, v135, s0
	v_cvt_pk_bf16_f32 v132, v132, s0
	global_store_short v[166:167], v128, off offset:1856
	v_cvt_pk_bf16_f32 v128, v131, s0
	global_store_short v[166:167], v132, off offset:320
	global_store_short v[166:167], v128, off offset:3904

.LBB0_1141:
	s_or_b64 exec, exec, s[4:5]
	v_mov_b32_e32 v163, v162
	v_mov_b32_e32 v132, v162
	v_mov_b32_e32 v133, v162
	v_lshl_add_u64 v[160:161], v[152:153], 0, v[160:161]
	v_mov_b32_e32 v155, v193
	v_pk_mul_f32 v[130:131], v[14:15], v[132:133]
	v_pk_mul_f32 v[128:129], v[12:13], v[162:163]
	v_pk_mul_f32 v[134:135], v[10:11], v[132:133]
	v_pk_mul_f32 v[132:133], v[8:9], v[162:163]
	v_lshl_add_u64 v[160:161], v[160:161], 0, v[154:155]
	v_mov_b32_e32 v184, v128
	v_mov_b32_e32 v185, v129
	v_mov_b32_e32 v186, v130
	v_mov_b32_e32 v187, v131
	v_mov_b32_e32 v188, v132
	v_mov_b32_e32 v189, v133
	v_mov_b32_e32 v190, v134
	v_mov_b32_e32 v191, v135
	s_nop 1
	v_permlane16_swap_b32_e32 v184, v188
	v_permlane16_swap_b32_e32 v185, v189
	v_permlane16_swap_b32_e32 v186, v190
	v_permlane16_swap_b32_e32 v187, v191
	s_nop 1
	v_permlane32_swap_b32_e32 v184, v188
	v_permlane32_swap_b32_e32 v185, v189
	v_permlane32_swap_b32_e32 v186, v190
	v_permlane32_swap_b32_e32 v187, v191
	v_lshl_add_u64 v[182:183], v[160:161], 0, v[178:179]
	global_store_dwordx4 v[182:183], v[184:187], off
	global_store_dwordx4 v[182:183], v[188:191], off offset:64
	s_and_saveexec_b64 s[4:5], s[0:1]
	s_xor_b64 s[4:5], exec, s[4:5]
	s_cbranch_execz .LBB0_1143
	v_mov_b32_e32 v147, v193
	v_lshl_add_u64 v[160:161], v[148:149], 0, v[146:147]
	v_lshl_add_u64 v[160:161], v[172:173], 1, v[160:161]
	v_cvt_pk_bf16_f32 v128, v128, s0
	global_store_short v[160:161], v128, off offset:320
	v_cvt_pk_bf16_f32 v128, v132, s0
	global_store_short v[160:161], v128, off offset:2368
	v_cvt_pk_bf16_f32 v128, v129, s0
	global_store_short v[160:161], v128, off offset:832
	v_cvt_pk_bf16_f32 v128, v133, s0
	global_store_short v[160:161], v128, off offset:2880
	v_cvt_pk_bf16_f32 v128, v130, s0
	global_store_short v[160:161], v128, off offset:1344
	v_cvt_pk_bf16_f32 v128, v134, s0
	global_store_short v[160:161], v128, off offset:3392
	v_cvt_pk_bf16_f32 v128, v131, s0
	global_store_short v[160:161], v128, off offset:1856
	v_cvt_pk_bf16_f32 v128, v135, s0
	global_store_short v[160:161], v128, off offset:3904

.LBB0_1145:
	s_or_b64 exec, exec, s[4:5]
	v_add_u32_e32 v164, 0xb0, v172
	v_add_u32_e32 v128, s63, v164
	v_ashrrev_i32_e32 v129, 31, v128
	v_lshl_add_u64 v[130:131], v[128:129], 2, s[90:91]
	global_load_dword v130, v[130:131], off
	v_lshlrev_b64 v[160:161], 12, v[128:129]
	v_mov_b32_e32 v139, v193
	v_lshl_add_u64 v[128:129], v[142:143], 0, v[160:161]
	v_lshl_add_u64 v[138:139], v[128:129], 0, v[138:139]
	s_waitcnt vmcnt(0) lgkmcnt(0)
	v_fmamk_f32 v130, v130, 0x3a800000, v215
	v_rsq_f32_e32 v162, v130
	s_nop 0
	v_pk_mul_f32 v[134:135], v[38:39], v[162:163] op_sel_hi:[1,0]
	v_pk_mul_f32 v[132:133], v[36:37], v[162:163] op_sel_hi:[1,0]
	v_pk_mul_f32 v[130:131], v[34:35], v[162:163] op_sel_hi:[1,0]
	v_pk_mul_f32 v[128:129], v[32:33], v[162:163] op_sel_hi:[1,0]
	v_mov_b32_e32 v184, v132
	v_mov_b32_e32 v185, v133
	v_mov_b32_e32 v186, v134
	v_mov_b32_e32 v187, v135
	v_mov_b32_e32 v188, v128
	v_mov_b32_e32 v189, v129
	v_mov_b32_e32 v190, v130
	v_mov_b32_e32 v191, v131
	s_nop 1
	v_permlane16_swap_b32_e32 v184, v188
	v_permlane16_swap_b32_e32 v185, v189
	v_permlane16_swap_b32_e32 v186, v190
	v_permlane16_swap_b32_e32 v187, v191
	s_nop 1
	v_permlane32_swap_b32_e32 v184, v188
	v_permlane32_swap_b32_e32 v185, v189
	v_permlane32_swap_b32_e32 v186, v190
	v_permlane32_swap_b32_e32 v187, v191
	v_lshl_add_u64 v[182:183], v[138:139], 0, v[178:179]
	global_store_dwordx4 v[182:183], v[184:187], off
	global_store_dwordx4 v[182:183], v[188:191], off offset:64
	s_and_saveexec_b64 s[4:5], vcc
	s_xor_b64 s[4:5], exec, s[4:5]
	s_cbranch_execz .LBB0_1147
	v_mov_b32_e32 v137, v193
	v_lshl_add_u64 v[136:137], v[140:141], 0, v[136:137]
	v_lshl_add_u64 v[136:137], v[172:173], 1, v[136:137]
	v_cvt_pk_bf16_f32 v128, v128, s0
	global_store_short v[136:137], v128, off offset:2400
	v_cvt_pk_bf16_f32 v128, v133, s0
	global_store_short v[136:137], v128, off offset:864
	v_cvt_pk_bf16_f32 v128, v129, s0
	global_store_short v[136:137], v128, off offset:2912
	v_cvt_pk_bf16_f32 v128, v134, s0
	global_store_short v[136:137], v128, off offset:1376
	v_cvt_pk_bf16_f32 v128, v130, s0
	global_store_short v[136:137], v128, off offset:3424
	v_cvt_pk_bf16_f32 v128, v135, s0
	v_cvt_pk_bf16_f32 v132, v132, s0
	global_store_short v[136:137], v128, off offset:1888
	v_cvt_pk_bf16_f32 v128, v131, s0
	global_store_short v[136:137], v132, off offset:352
	global_store_short v[136:137], v128, off offset:3936

.LBB0_1149:
	s_or_b64 exec, exec, s[4:5]
	v_mov_b32_e32 v163, v162
	v_mov_b32_e32 v132, v162
	v_mov_b32_e32 v133, v162
	v_lshl_add_u64 v[138:139], v[152:153], 0, v[160:161]
	v_mov_b32_e32 v155, v193
	v_pk_mul_f32 v[130:131], v[6:7], v[132:133]
	v_pk_mul_f32 v[128:129], v[4:5], v[162:163]
	v_pk_mul_f32 v[134:135], v[2:3], v[132:133]
	v_pk_mul_f32 v[132:133], v[0:1], v[162:163]
	v_lshl_add_u64 v[138:139], v[138:139], 0, v[154:155]
	v_mov_b32_e32 v184, v128
	v_mov_b32_e32 v185, v129
	v_mov_b32_e32 v186, v130
	v_mov_b32_e32 v187, v131
	v_mov_b32_e32 v188, v132
	v_mov_b32_e32 v189, v133
	v_mov_b32_e32 v190, v134
	v_mov_b32_e32 v191, v135
	s_nop 1
	v_permlane16_swap_b32_e32 v184, v188
	v_permlane16_swap_b32_e32 v185, v189
	v_permlane16_swap_b32_e32 v186, v190
	v_permlane16_swap_b32_e32 v187, v191
	s_nop 1
	v_permlane32_swap_b32_e32 v184, v188
	v_permlane32_swap_b32_e32 v185, v189
	v_permlane32_swap_b32_e32 v186, v190
	v_permlane32_swap_b32_e32 v187, v191
	v_lshl_add_u64 v[182:183], v[138:139], 0, v[178:179]
	global_store_dwordx4 v[182:183], v[184:187], off
	global_store_dwordx4 v[182:183], v[188:191], off offset:64
	s_and_saveexec_b64 s[4:5], s[0:1]
	s_xor_b64 s[0:1], exec, s[4:5]
	s_cbranch_execz .LBB0_1151
	v_mov_b32_e32 v147, v193
	v_lshl_add_u64 v[136:137], v[148:149], 0, v[146:147]
	v_lshl_add_u64 v[136:137], v[172:173], 1, v[136:137]
	v_cvt_pk_bf16_f32 v128, v128, s0
	global_store_short v[136:137], v128, off offset:352
	v_cvt_pk_bf16_f32 v128, v132, s0
	global_store_short v[136:137], v128, off offset:2400
	v_cvt_pk_bf16_f32 v128, v129, s0
	global_store_short v[136:137], v128, off offset:864
	v_cvt_pk_bf16_f32 v128, v133, s0
	global_store_short v[136:137], v128, off offset:2912
	v_cvt_pk_bf16_f32 v128, v130, s0
	global_store_short v[136:137], v128, off offset:1376
	v_cvt_pk_bf16_f32 v128, v134, s0
	global_store_short v[136:137], v128, off offset:3424
	v_cvt_pk_bf16_f32 v128, v131, s0
	global_store_short v[136:137], v128, off offset:1888
	v_cvt_pk_bf16_f32 v128, v135, s0
	global_store_short v[136:137], v128, off offset:3936
